# static s_setprio 1 for waves 4-7 also in the S1 and MoBA gate phases, placement-preserving
# speedup vs baseline: 1.0122x; 1.0001x over previous
; #define LAS __attribute__((address_space(3)))
; __device__ __forceinline__ void ssd_s1_phase(Frame& F, const bf16* xtile, const bf16* btT, const float* dt, const float* a_log, bf16* states, float* decay) {
;     const int lane = F.lane, h2 = lane >> 5;
;     LAS float* w1 = (LAS float*)(F.lds + RING_OFF) + F.wave * 256;
;     LAS unsigned char* BL = F.lds + RING_OFF + 16384;
;     for (int u = blockIdx.x; u < 64 * SSD_NG; u += F.G) {
;         const int c = u >> 3, g = u & 7, t0 = c * 128;
;         float dec_out[2];
; #pragma unroll
;         for (int hh = 0; hh < 2; ++hh) { const int h = g * 16 + F.wave * 2 + hh; const float A = -__expf(a_log[h]);
;             const float d0 = dt[(size_t)(t0 + 2 * lane) * 128 + h], d1 = dt[(size_t)(t0 + 2 * lane + 1) * 128 + h];
;             const float a0 = d0 * A, a1 = d1 * A; float s = a0 + a1;
; #pragma unroll
;             for (int o = 1; o < 64; o <<= 1) { const float v = __shfl_up(s, o); if (lane >= o) s += v; }
;             const float cs1 = s, cs0 = s - a1; const float cend = __shfl(s, 63);
;             w1[hh * 128 + 2 * lane] = d0 * __expf(cend - cs0); w1[hh * 128 + 2 * lane + 1] = d1 * __expf(cend - cs1);
;             dec_out[hh] = __expf(cend); }
;         if (lane == 0) { decay[(c * 8 + g) * 32 + F.wave * 2] = dec_out[0]; decay[(c * 8 + g) * 32 + F.wave * 2 + 1] = dec_out[1]; }
;         __syncthreads();
;         { const bf16* bp = btT + ((((size_t)c * 8 + g) * 4) * 8) * 512 + (size_t)lane * 8; v4u bq[4];
.LBB0_427:
	s_cmpk_ge_u32 s94, 0x100
	s_cbranch_scc0 .Lprio_skip_s1a
	s_setprio 1
.Lprio_skip_s1a:
	s_load_dwordx2 s[2:3], s[74:75], 0x100
	s_waitcnt lgkmcnt(0)
	s_cmp_lt_i32 s2, 4
	s_cselect_b64 s[2:3], -1, 0
	s_and_b64 s[28:29], s[2:3], s[0:1]
	s_andn2_b64 vcc, exec, s[28:29]
	s_cbranch_vccnz .LBB0_437
	s_mov_b32 s0, 48
	s_cmpk_gt_i32 s93, 0x1ff
	s_cbranch_scc1 .LBB0_437
	s_add_u32 s30, s78, 0x54300000
	s_addc_u32 s31, s79, 0
	s_add_u32 s33, s78, 0x5c300000
	s_addc_u32 s46, s79, 0
	s_add_u32 s34, s78, 0x6a300000
	s_addc_u32 s35, s79, 0
	s_ashr_i32 s1, s0, 31
	s_add_u32 s0, s74, s0
	s_addc_u32 s1, s75, s1
	s_add_u32 s47, s78, 0x4c300000
	s_addc_u32 s48, s79, 0
	s_load_dwordx2 s[36:37], s[0:1], 0x0
	s_add_u32 s49, s78, 0x6a780000
	v_readlane_b32 s0, v251, 8
	v_mbcnt_lo_u32_b32 v2, -1, 0
	s_addc_u32 s50, s79, 0
	s_mov_b32 s16, s0
	s_lshl_b32 s0, s0, 10
	v_mbcnt_hi_u32_b32 v2, -1, v2
	v_bfrev_b32_e32 v4, 0.5
	v_mov_b32_e32 v149, 0
	s_add_i32 s2, s0, 0
	v_lshl_or_b32 v147, v2, 2, v4
	v_lshlrev_b32_e32 v150, 4, v186
	v_mov_b32_e32 v151, v149
	v_and_b32_e32 v4, 32, v0
	v_and_b32_e32 v3, 64, v2
	v_lshl_add_u64 v[152:153], s[30:31], 0, v[150:151]
	v_add_u32_e32 v151, s2, v4
	v_add_u32_e32 v4, -1, v2
	v_cmp_lt_i32_e32 vcc, v4, v3
	s_mov_b32 s13, 0
	s_lshl_b32 s12, s16, 2
	v_cndmask_b32_e32 v4, v4, v2, vcc
	v_lshlrev_b32_e32 v156, 2, v4
	v_add_u32_e32 v4, -2, v2
	v_cmp_lt_i32_e32 vcc, v4, v3
	s_or_b32 s14, s12, 1
	s_mov_b32 s15, s13
	v_cndmask_b32_e32 v4, v4, v2, vcc
	v_lshlrev_b32_e32 v157, 2, v4
	v_add_u32_e32 v4, -4, v2
	v_cmp_lt_i32_e32 vcc, v4, v3
	s_lshl_b64 s[38:39], s[12:13], 10
	s_lshl_b64 s[40:41], s[14:15], 10
	v_cndmask_b32_e32 v4, v4, v2, vcc
	v_lshlrev_b32_e32 v158, 2, v4
	v_add_u32_e32 v4, -8, v2
	v_cmp_lt_i32_e32 vcc, v4, v3
	s_or_b32 s14, s12, 2
	s_or_b32 s12, s12, 3
	v_cndmask_b32_e32 v4, v4, v2, vcc
	v_lshlrev_b32_e32 v159, 2, v4
	v_add_u32_e32 v4, -16, v2
	v_cmp_lt_i32_e32 vcc, v4, v3
	s_lshl_b64 s[44:45], s[12:13], 10
	s_mov_b32 s12, s13
	v_cndmask_b32_e32 v4, v4, v2, vcc
	v_lshlrev_b32_e32 v160, 2, v4
	v_subrev_u32_e32 v4, 32, v2
	v_cmp_lt_i32_e32 vcc, v4, v3
	v_readlane_b32 s1, v251, 9
	v_lshlrev_b32_e32 v146, 3, v186
	v_cndmask_b32_e32 v2, v4, v2, vcc
	v_lshlrev_b32_e32 v161, 2, v2
	s_lshl_b32 s51, s16, 1
	s_lshl_b64 s[42:43], s[14:15], 10
	s_lshl_b32 s52, s16, 12
	s_mov_b32 s14, s13
	s_mov_b32 s16, s13
	s_mov_b32 s17, s13
	s_mov_b32 s18, s13
	s_mov_b32 s19, s13
	s_mov_b32 s20, s13
	s_mov_b32 s21, s13
	s_mov_b32 s22, s13
	s_mov_b32 s23, s13
	s_mov_b32 s24, s13
	s_mov_b32 s25, s13
	s_mov_b32 s26, s13
	s_mov_b32 s27, s13
	v_mov_b64_e32 v[2:3], s[12:13]
	v_lshlrev_b32_e32 v1, 1, v186
	v_add_u32_e32 v154, s2, v146
	v_cmp_eq_u32_e64 s[0:1], 0, v186
	v_add_u32_e32 v155, 0, v150
	v_cmp_gt_u32_e64 s[2:3], 2, v186
	v_cmp_gt_u32_e64 s[4:5], 4, v186
	v_cmp_gt_u32_e64 s[6:7], 8, v186
	v_cmp_gt_u32_e64 s[8:9], 16, v186
	v_cmp_gt_u32_e64 s[10:11], 32, v186
	s_add_i32 s53, s52, 0
	s_movk_i32 s54, 0x1000
	v_mov_b64_e32 v[4:5], s[14:15]
	v_mov_b64_e32 v[6:7], s[16:17]
	v_mov_b64_e32 v[8:9], s[18:19]
	v_mov_b64_e32 v[10:11], s[20:21]
	v_mov_b64_e32 v[12:13], s[22:23]
	v_mov_b64_e32 v[14:15], s[24:25]
	v_mov_b64_e32 v[16:17], s[26:27]
	s_mov_b32 s18, s93
	s_branch .LBB0_431

; __device__ __forceinline__ unsigned xb_add(unsigned* p, unsigned v) { return __hip_atomic_fetch_add(p, v, __ATOMIC_RELAXED, __HIP_MEMORY_SCOPE_AGENT); }
; __device__ __forceinline__ void xcd_barrier(const XcdBarrier& b) {
;     asm volatile("s_waitcnt vmcnt(0)" ::: "memory");
;     __syncthreads();
;     if (threadIdx.x == 0) {
;         unsigned* bar = b.bar;
;         __builtin_amdgcn_s_waitcnt(0);
;         unsigned nloc = b.st[0], nx = b.st[1];
;         if (nloc == 0u) { xcd_barrier_complete(bar, b.x, nloc, nx); b.st[0] = nloc; b.st[1] = nx; }
;         const unsigned old = xb_add(&bar[XB_XSUB(b.x)], 1u);
.LBB0_437:
	s_setprio 0
	s_nop 0
	s_nop 0
	s_nop 0
	s_nop 0
	s_nop 0
	s_nop 0
	s_nop 0
	s_nop 0
	s_nop 0
	s_nop 0
	s_nop 0
	s_nop 0
	s_nop 0
	s_nop 0
	s_nop 0
	s_nop 0
	s_nop 0
	s_nop 0
	s_nop 0
	s_nop 0
	s_nop 0
	s_nop 0
	s_nop 0
	s_nop 0
	s_nop 0
	s_nop 0
	s_nop 0
	s_nop 0
	s_load_dwordx2 s[0:1], s[74:75], 0x100
	s_waitcnt lgkmcnt(0)
	s_cmp_gt_i32 s1, 4
	s_cselect_b64 s[0:1], -1, 0
	s_and_b64 s[2:3], s[28:29], s[0:1]
	s_andn2_b64 vcc, exec, s[2:3]
	s_cbranch_vccnz .LBB0_487
	s_waitcnt vmcnt(0)
	v_cmp_eq_u32_e32 vcc, 0, v0
	s_barrier
	s_and_saveexec_b64 s[2:3], vcc
	s_cbranch_execz .LBB0_486
	v_readlane_b32 s4, v251, 7
	s_waitcnt vmcnt(0) expcnt(0) lgkmcnt(0)
	s_nop 0
	v_mov_b32_e32 v1, s4
	ds_read_b32 v3, v1
	ds_read_b32 v1, v1 offset:4
	s_waitcnt lgkmcnt(1)
	v_cmp_ne_u32_e32 vcc, 0, v3
	s_cbranch_vccnz .LBB0_454
	v_readlane_b32 s4, v251, 2
	v_readlane_b32 s5, v251, 3
	s_load_dwordx2 s[8:9], s[4:5], 0x4
	s_load_dword s10, s[74:75], 0x108
	s_add_u32 s4, s78, 0x4200
	s_addc_u32 s5, s79, 0
	s_add_u32 s6, s78, 0x4400
	s_addc_u32 s7, s79, 0
	s_waitcnt lgkmcnt(0)
	s_mul_i32 s33, s8, s10
	s_add_u32 s8, s78, 0x4500
	s_mul_i32 s33, s33, s9
	s_addc_u32 s9, s79, 0
	s_add_u32 s10, s78, 0x4600
	s_addc_u32 s11, s79, 0
	s_add_u32 s12, s78, 0x4700
	s_addc_u32 s13, s79, 0
	s_add_u32 s14, s78, 0x4800
	s_addc_u32 s15, s79, 0
	s_add_u32 s16, s78, 0x4900
	s_addc_u32 s17, s79, 0
	s_add_u32 s18, s78, 0x4a00
	s_addc_u32 s19, s79, 0
	s_add_u32 s20, s78, 0x4b00
	s_addc_u32 s21, s79, 0
	s_add_u32 s22, s78, 0x4c00
	s_addc_u32 s23, s79, 0
	s_add_u32 s24, s78, 0x4d00
	s_addc_u32 s25, s79, 0
	s_add_u32 s26, s78, 0x4e00
	s_addc_u32 s27, s79, 0
	s_add_u32 s28, s78, 0x4f00
	s_addc_u32 s29, s79, 0
	s_add_u32 s30, s78, 0x5000
	s_addc_u32 s31, s79, 0
	s_add_u32 s34, s78, 0x5100
	s_addc_u32 s35, s79, 0
	s_add_u32 s36, s78, 0x5200
	s_addc_u32 s37, s79, 0
	s_add_u32 s38, s78, 0x5300
	s_addc_u32 s39, s79, 0
	s_mov_b32 s46, 1
	v_mov_b32_e32 v17, 0
	s_branch .LBB0_442

; #define LAS __attribute__((address_space(3)))
; __device__ __forceinline__ void moba_gate_phase(Frame& F, const bf16* qkvg, const bf16* kmb, int* cntg, unsigned short* listg, unsigned char* selvg) {
;     const int lane = F.lane, r = lane & 31, h2 = lane >> 5;
;     LAS unsigned short* LIST = (LAS unsigned short*)(F.lds + RING_OFF);
;     LAS int* CNTW = (LAS int*)(F.lds + RING_OFF + 16384);
;     LAS int* TOT = (LAS int*)(F.lds + RING_OFF + 17408);
;     for (int u = blockIdx.x; u < MOBA_H * MOBA_NB; u += F.G) {
;         const int h = u >> 5, j = u & 31;
;         int s0 = -1, s1 = -1, s2 = -1;
;         { const bf16* qp = qkvg + (size_t)(j * 256 + F.wave * 32 + r) * 16384 + h * 128 + h2 * 8; const bf16* kp = kmb + ((size_t)h * MOBA_NB + r) * 128 + h2 * 8;
;           f32x16 gs = zero16();
; #pragma unroll
;           for (int ks = 0; ks < 8; ++ks) { const bf16x8 a = *(const bf16x8*)(kp + ks * 16), b = *(const bf16x8*)(qp + ks * 16); gs = __builtin_amdgcn_mfma_f32_32x32x16_bf16(a, b, gs, 0, 0, 0); }
;           float v0 = -INFINITY, v1 = -INFINITY, v2 = -INFINITY;
; #pragma unroll
;           for (int n = 0; n < 32; ++n) { const int ri = (n & 3) + 4 * (n >> 3); const float own = gs[ri], oth = other_half(own, h2 != 0);
;               float s = (((n >> 2) & 1) == h2) ? own : oth; if (n >= j) s = -INFINITY;
;               if (s > v0) { v2 = v1; s2 = s1; v1 = v0; s1 = s0; v0 = s; s0 = n; } else if (s > v1) { v2 = v1; s2 = s1; v1 = s; s1 = n; } else if (s > v2) { v2 = s; s2 = n; } }
;         }
;         if (h2 == 0) selvg[(size_t)(j * 256 + F.wave * 32 + r) * MOBA_H + h] = (unsigned char)((s0 >= 0 ? 1 : 0) | (s1 >= 0 ? 2 : 0) | (s2 >= 0 ? 4 : 0));
.LBB0_1339:
	s_cmpk_ge_u32 s94, 0x100
	s_cbranch_scc0 .Lprio_skip_gt
	s_setprio 1
.Lprio_skip_gt:
	s_load_dwordx2 s[2:3], s[74:75], 0x100
	s_waitcnt lgkmcnt(0)
	s_cmp_lt_i32 s2, 15
	s_cselect_b64 s[2:3], -1, 0
	s_and_b64 s[24:25], s[2:3], s[0:1]
	s_andn2_b64 vcc, exec, s[24:25]
	s_cbranch_vccnz .LBB0_1551
	s_cmpk_gt_i32 s93, 0x3ff
	s_cbranch_scc1 .LBB0_1551
	s_add_u32 s26, s78, 0x32300000
	s_addc_u32 s27, s79, 0
	s_add_u32 s28, s78, 0x64b00000
	s_addc_u32 s29, s79, 0
	s_add_u32 s30, s78, 0x64c00000
	v_lshrrev_b32_e32 v1, 2, v0
	v_readlane_b32 s4, v251, 8
	s_addc_u32 s31, s79, 0
	v_and_b32_e32 v18, 8, v1
	s_lshl_b32 s33, s4, 5
	s_lshl_b32 s18, s4, 7
	v_mov_b32_e32 v37, 0
	v_lshlrev_b32_e32 v36, 1, v18
	s_cmp_lt_u32 s94, 64
	v_lshl_add_u64 v[2:3], s[78:79], 0, v[36:37]
	s_mov_b64 s[0:1], 0x6a700000
	v_readlane_b32 s5, v251, 9
	s_cselect_b64 s[36:37], -1, 0
	s_cmpk_gt_u32 s94, 0x7f
	v_lshl_add_u64 v[38:39], v[2:3], 0, s[0:1]
	v_lshlrev_b64 v[2:3], v186, -1
	s_cselect_b64 s[4:5], -1, 0
	s_cmpk_gt_u32 s94, 0xbf
	v_not_b32_e32 v40, v2
	s_cselect_b64 s[6:7], -1, 0
	s_cmpk_gt_u32 s94, 0xff
	v_lshrrev_b32_e32 v2, 8, v0
	v_not_b32_e32 v1, v3
	s_cselect_b64 s[8:9], -1, 0
	s_cmpk_gt_u32 s94, 0x13f
	v_lshl_add_u32 v3, v2, 2, 0
	s_cselect_b64 s[10:11], -1, 0
	s_cmpk_gt_u32 s94, 0x17f
	v_add_u32_e32 v46, 0x4400, v3
	v_mov_b32_e32 v3, 1
	s_cselect_b64 s[12:13], -1, 0
	s_cmpk_gt_u32 s94, 0x1bf
	v_lshlrev_b32_sdwa v3, v3, v0 dst_sel:DWORD dst_unused:UNUSED_PAD src0_sel:DWORD src1_sel:BYTE_0
	s_cselect_b64 s[14:15], -1, 0
	s_cmpk_gt_u32 s94, 0x1ff
	v_lshl_or_b32 v36, v2, 14, v3
	v_cmp_gt_u32_e64 s[0:1], 32, v186
	s_cselect_b64 s[16:17], -1, 0
	s_add_i32 s48, s18, 0
	v_lshl_add_u64 v[2:3], s[78:79], 0, v[36:37]
	s_mov_b64 s[18:19], 0x64d00000
	v_and_b32_e32 v34, 31, v0
	v_cmp_lt_u32_e32 vcc, 31, v186
	s_mov_b32 s35, 0
	v_cmp_eq_u32_e64 s[2:3], 0, v186
	v_lshl_add_u32 v35, v186, 2, 0
	s_and_b64 s[38:39], s[0:1], s[36:37]
	v_or_b32_e32 v41, s33, v186
	s_addk_i32 s48, 0x4000
	v_lshl_add_u64 v[42:43], v[2:3], 0, s[18:19]
	v_lshl_add_u32 v47, v0, 1, 0
	v_or_b32_e32 v48, 0xfffffe00, v0
	v_mov_b32_e32 v2, v37
	v_mov_b32_e32 v3, v37
	v_mov_b32_e32 v4, v37
	v_mov_b32_e32 v5, v37
	v_mov_b32_e32 v6, v37
	v_mov_b32_e32 v7, v37
	v_mov_b32_e32 v8, v37
	v_mov_b32_e32 v9, v37
	v_mov_b32_e32 v10, v37
	v_mov_b32_e32 v11, v37
	v_mov_b32_e32 v12, v37
	v_mov_b32_e32 v13, v37
	v_mov_b32_e32 v14, v37
	v_mov_b32_e32 v15, v37
	v_mov_b32_e32 v16, v37
	v_mov_b32_e32 v17, v37
	s_mov_b32 s49, 0xff800000
	v_mov_b32_e32 v49, 0xff800000
	s_mov_b64 s[40:41], 0x8000
	s_movk_i32 s50, 0x1dff
	v_lshlrev_b32_e32 v44, 1, v18
	v_mov_b32_e32 v45, v37
	v_mov_b32_e32 v50, 0x200
	v_mov_b32_e32 v51, 0x100
	s_mov_b32 s51, s93
	s_mov_b32 s52, s93
	s_branch .LBB0_1343

; __device__ __forceinline__ unsigned xb_add(unsigned* p, unsigned v) { return __hip_atomic_fetch_add(p, v, __ATOMIC_RELAXED, __HIP_MEMORY_SCOPE_AGENT); }
; #define SEAM(k) do { if (IN(k) && IN((k) + 1)) xcd_barrier(bar); } while (0)
; __device__ __forceinline__ void xcd_barrier(const XcdBarrier& b) {
;     asm volatile("s_waitcnt vmcnt(0)" ::: "memory");
;     __syncthreads();
;     if (threadIdx.x == 0) {
;         unsigned* bar = b.bar;
;         __builtin_amdgcn_s_waitcnt(0);
;         unsigned nloc = b.st[0], nx = b.st[1];
;         if (nloc == 0u) { xcd_barrier_complete(bar, b.x, nloc, nx); b.st[0] = nloc; b.st[1] = nx; }
;         const unsigned old = xb_add(&bar[XB_XSUB(b.x)], 1u);
; __global__ void __launch_bounds__(NWAVES * 64, 2) mk_fwd(Args args) {
;     ...
;             if (IN(14)) moba_gate_phase(F, WSP(const bf16, WS_ACT_A), WSP(const bf16, WS_KMEAN), WSP(int, WS_XC + 136 * MiB), WSP(unsigned short, WS_XC + 138 * MiB), WSP(unsigned char, WS_XC + 137 * MiB));
;             SEAM(14);
.LBB0_1551:
	s_setprio 0
	s_nop 0
	s_nop 0
	s_nop 0
	s_nop 0
	s_nop 0
	s_nop 0
	s_nop 0
	s_nop 0
	s_nop 0
	s_nop 0
	s_nop 0
	s_nop 0
	s_nop 0
	s_nop 0
	s_nop 0
	s_nop 0
	s_nop 0
	s_nop 0
	s_nop 0
	s_nop 0
	s_nop 0
	s_nop 0
	s_nop 0
	s_nop 0
	s_nop 0
	s_nop 0
	s_nop 0
	s_nop 0
	s_load_dwordx2 s[0:1], s[74:75], 0x100
	s_waitcnt lgkmcnt(0)
	s_cmp_gt_i32 s1, 15
	s_cselect_b64 s[0:1], -1, 0
	s_and_b64 s[2:3], s[24:25], s[0:1]
	s_andn2_b64 vcc, exec, s[2:3]
	s_cbranch_vccnz .LBB0_1601
	s_waitcnt vmcnt(0)
	v_cmp_eq_u32_e32 vcc, 0, v0
	s_waitcnt vmcnt(0)
	s_barrier
	s_and_saveexec_b64 s[2:3], vcc
	s_cbranch_execz .LBB0_1600
	v_readlane_b32 s4, v251, 7
	s_waitcnt vmcnt(0) expcnt(0) lgkmcnt(0)
	s_nop 0
	v_mov_b32_e32 v1, s4
	ds_read_b32 v3, v1
	ds_read_b32 v1, v1 offset:4
	s_waitcnt lgkmcnt(1)
	v_cmp_ne_u32_e32 vcc, 0, v3
	s_cbranch_vccnz .LBB0_1568
	v_readlane_b32 s4, v251, 2
	v_readlane_b32 s5, v251, 3
	s_load_dwordx2 s[8:9], s[4:5], 0x4
	s_load_dword s10, s[74:75], 0x108
	s_add_u32 s4, s78, 0x4200
	s_addc_u32 s5, s79, 0
	s_add_u32 s6, s78, 0x4400
	s_addc_u32 s7, s79, 0
	s_waitcnt lgkmcnt(0)
	s_mul_i32 s33, s8, s10
	s_add_u32 s8, s78, 0x4500
	s_mul_i32 s33, s33, s9
	s_addc_u32 s9, s79, 0
	s_add_u32 s10, s78, 0x4600
	s_addc_u32 s11, s79, 0
	s_add_u32 s12, s78, 0x4700
	s_addc_u32 s13, s79, 0
	s_add_u32 s14, s78, 0x4800
	s_addc_u32 s15, s79, 0
	s_add_u32 s16, s78, 0x4900
	s_addc_u32 s17, s79, 0
	s_add_u32 s18, s78, 0x4a00
	s_addc_u32 s19, s79, 0
	s_add_u32 s20, s78, 0x4b00
	s_addc_u32 s21, s79, 0
	s_add_u32 s22, s78, 0x4c00
	s_addc_u32 s23, s79, 0
	s_add_u32 s24, s78, 0x4d00
	s_addc_u32 s25, s79, 0
	s_add_u32 s26, s78, 0x4e00
	s_addc_u32 s27, s79, 0
	s_add_u32 s28, s78, 0x4f00
	s_addc_u32 s29, s79, 0
	s_add_u32 s30, s78, 0x5000
	s_addc_u32 s31, s79, 0
	s_add_u32 s34, s78, 0x5100
	s_addc_u32 s35, s79, 0
	s_add_u32 s36, s78, 0x5200
	s_addc_u32 s37, s79, 0
	s_add_u32 s38, s78, 0x5300
	s_addc_u32 s39, s79, 0
	s_mov_b32 s46, 1
	v_mov_b32_e32 v17, 0
	s_branch .LBB0_1556

; #define LAS __attribute__((address_space(3)))
; __device__ __forceinline__ void ssd_s1_phase(Frame& F, const bf16* xtile, const bf16* btT, const float* dt, const float* a_log, bf16* states, float* decay) {
;     const int lane = F.lane, h2 = lane >> 5;
;     LAS float* w1 = (LAS float*)(F.lds + RING_OFF) + F.wave * 256;
;     LAS unsigned char* BL = F.lds + RING_OFF + 16384;
;     for (int u = blockIdx.x; u < 64 * SSD_NG; u += F.G) {
;         const int c = u >> 3, g = u & 7, t0 = c * 128;
;         float dec_out[2];
; #pragma unroll
;         for (int hh = 0; hh < 2; ++hh) { const int h = g * 16 + F.wave * 2 + hh; const float A = -__expf(a_log[h]);
;             const float d0 = dt[(size_t)(t0 + 2 * lane) * 128 + h], d1 = dt[(size_t)(t0 + 2 * lane + 1) * 128 + h];
;             const float a0 = d0 * A, a1 = d1 * A; float s = a0 + a1;
; #pragma unroll
;             for (int o = 1; o < 64; o <<= 1) { const float v = __shfl_up(s, o); if (lane >= o) s += v; }
;             const float cs1 = s, cs0 = s - a1; const float cend = __shfl(s, 63);
;             w1[hh * 128 + 2 * lane] = d0 * __expf(cend - cs0); w1[hh * 128 + 2 * lane + 1] = d1 * __expf(cend - cs1);
;             dec_out[hh] = __expf(cend); }
;         if (lane == 0) { decay[(c * 8 + g) * 32 + F.wave * 2] = dec_out[0]; decay[(c * 8 + g) * 32 + F.wave * 2 + 1] = dec_out[1]; }
;         __syncthreads();
;         { const bf16* bp = btT + ((((size_t)c * 8 + g) * 4) * 8) * 512 + (size_t)lane * 8; v4u bq[4];
.LBB0_2134:
	s_cmpk_ge_u32 s94, 0x100
	s_cbranch_scc0 .Lprio_skip_s1b
	s_setprio 1
.Lprio_skip_s1b:
	s_load_dwordx2 s[2:3], s[74:75], 0x100
	s_waitcnt lgkmcnt(0)
	s_cmp_lt_i32 s2, 21
	s_cselect_b64 s[2:3], -1, 0
	s_and_b64 s[28:29], s[2:3], s[0:1]
	s_andn2_b64 vcc, exec, s[28:29]
	s_cbranch_vccnz .LBB0_2144
	s_movk_i32 s0, 0xd0
	s_cmpk_gt_i32 s93, 0x1ff
	s_cbranch_scc1 .LBB0_2144
	s_add_u32 s30, s78, 0x54300000
	s_addc_u32 s31, s79, 0
	s_add_u32 s33, s78, 0x5c300000
	s_addc_u32 s46, s79, 0
	s_add_u32 s34, s78, 0x6a300000
	s_addc_u32 s35, s79, 0
	s_ashr_i32 s1, s0, 31
	s_add_u32 s0, s74, s0
	s_addc_u32 s1, s75, s1
	s_add_u32 s47, s78, 0x4c300000
	s_addc_u32 s48, s79, 0
	s_load_dwordx2 s[36:37], s[0:1], 0x0
	s_add_u32 s49, s78, 0x6a780000
	v_readlane_b32 s0, v251, 8
	v_mbcnt_lo_u32_b32 v2, -1, 0
	s_addc_u32 s50, s79, 0
	s_mov_b32 s16, s0
	s_lshl_b32 s0, s0, 10
	v_mbcnt_hi_u32_b32 v2, -1, v2
	v_bfrev_b32_e32 v4, 0.5
	v_mov_b32_e32 v149, 0
	s_add_i32 s2, s0, 0
	v_lshl_or_b32 v147, v2, 2, v4
	v_lshlrev_b32_e32 v150, 4, v186
	v_mov_b32_e32 v151, v149
	v_and_b32_e32 v4, 32, v0
	v_and_b32_e32 v3, 64, v2
	v_lshl_add_u64 v[152:153], s[30:31], 0, v[150:151]
	v_add_u32_e32 v151, s2, v4
	v_add_u32_e32 v4, -1, v2
	v_cmp_lt_i32_e32 vcc, v4, v3
	s_mov_b32 s13, 0
	s_lshl_b32 s12, s16, 2
	v_cndmask_b32_e32 v4, v4, v2, vcc
	v_lshlrev_b32_e32 v156, 2, v4
	v_add_u32_e32 v4, -2, v2
	v_cmp_lt_i32_e32 vcc, v4, v3
	s_or_b32 s14, s12, 1
	s_mov_b32 s15, s13
	v_cndmask_b32_e32 v4, v4, v2, vcc
	v_lshlrev_b32_e32 v157, 2, v4
	v_add_u32_e32 v4, -4, v2
	v_cmp_lt_i32_e32 vcc, v4, v3
	s_lshl_b64 s[38:39], s[12:13], 10
	s_lshl_b64 s[40:41], s[14:15], 10
	v_cndmask_b32_e32 v4, v4, v2, vcc
	v_lshlrev_b32_e32 v158, 2, v4
	v_add_u32_e32 v4, -8, v2
	v_cmp_lt_i32_e32 vcc, v4, v3
	s_or_b32 s14, s12, 2
	s_or_b32 s12, s12, 3
	v_cndmask_b32_e32 v4, v4, v2, vcc
	v_lshlrev_b32_e32 v159, 2, v4
	v_add_u32_e32 v4, -16, v2
	v_cmp_lt_i32_e32 vcc, v4, v3
	s_lshl_b64 s[44:45], s[12:13], 10
	s_mov_b32 s12, s13
	v_cndmask_b32_e32 v4, v4, v2, vcc
	v_lshlrev_b32_e32 v160, 2, v4
	v_subrev_u32_e32 v4, 32, v2
	v_cmp_lt_i32_e32 vcc, v4, v3
	v_readlane_b32 s1, v251, 9
	v_lshlrev_b32_e32 v146, 3, v186
	v_cndmask_b32_e32 v2, v4, v2, vcc
	v_lshlrev_b32_e32 v161, 2, v2
	s_lshl_b32 s51, s16, 1
	s_lshl_b64 s[42:43], s[14:15], 10
	s_lshl_b32 s52, s16, 12
	s_mov_b32 s14, s13
	s_mov_b32 s16, s13
	s_mov_b32 s17, s13
	s_mov_b32 s18, s13
	s_mov_b32 s19, s13
	s_mov_b32 s20, s13
	s_mov_b32 s21, s13
	s_mov_b32 s22, s13
	s_mov_b32 s23, s13
	s_mov_b32 s24, s13
	s_mov_b32 s25, s13
	s_mov_b32 s26, s13
	s_mov_b32 s27, s13
	v_mov_b64_e32 v[2:3], s[12:13]
	v_lshlrev_b32_e32 v1, 1, v186
	v_add_u32_e32 v154, s2, v146
	v_cmp_eq_u32_e64 s[0:1], 0, v186
	v_add_u32_e32 v155, 0, v150
	v_cmp_gt_u32_e64 s[2:3], 2, v186
	v_cmp_gt_u32_e64 s[4:5], 4, v186
	v_cmp_gt_u32_e64 s[6:7], 8, v186
	v_cmp_gt_u32_e64 s[8:9], 16, v186
	v_cmp_gt_u32_e64 s[10:11], 32, v186
	s_add_i32 s53, s52, 0
	s_movk_i32 s54, 0x1000
	v_mov_b64_e32 v[4:5], s[14:15]
	v_mov_b64_e32 v[6:7], s[16:17]
	v_mov_b64_e32 v[8:9], s[18:19]
	v_mov_b64_e32 v[10:11], s[20:21]
	v_mov_b64_e32 v[12:13], s[22:23]
	v_mov_b64_e32 v[14:15], s[24:25]
	v_mov_b64_e32 v[16:17], s[26:27]
	s_mov_b32 s18, s93
	s_branch .LBB0_2138

; __device__ __forceinline__ unsigned xb_add(unsigned* p, unsigned v) { return __hip_atomic_fetch_add(p, v, __ATOMIC_RELAXED, __HIP_MEMORY_SCOPE_AGENT); }
; __device__ __forceinline__ void xcd_barrier(const XcdBarrier& b) {
;     asm volatile("s_waitcnt vmcnt(0)" ::: "memory");
;     __syncthreads();
;     if (threadIdx.x == 0) {
;         unsigned* bar = b.bar;
;         __builtin_amdgcn_s_waitcnt(0);
;         unsigned nloc = b.st[0], nx = b.st[1];
;         if (nloc == 0u) { xcd_barrier_complete(bar, b.x, nloc, nx); b.st[0] = nloc; b.st[1] = nx; }
;         const unsigned old = xb_add(&bar[XB_XSUB(b.x)], 1u);
.LBB0_2144:
	s_setprio 0
	s_nop 0
	s_nop 0
	s_nop 0
	s_nop 0
	s_nop 0
	s_nop 0
	s_nop 0
	s_nop 0
	s_nop 0
	s_nop 0
	s_nop 0
	s_nop 0
	s_nop 0
	s_nop 0
	s_nop 0
	s_nop 0
	s_nop 0
	s_nop 0
	s_nop 0
	s_nop 0
	s_nop 0
	s_nop 0
	s_nop 0
	s_nop 0
	s_nop 0
	s_nop 0
	s_nop 0
	s_nop 0
	s_load_dwordx2 s[0:1], s[74:75], 0x100
	s_waitcnt lgkmcnt(0)
	s_cmp_gt_i32 s1, 21
	s_cselect_b64 s[0:1], -1, 0
	s_and_b64 s[2:3], s[28:29], s[0:1]
	s_andn2_b64 vcc, exec, s[2:3]
	s_cbranch_vccnz .LBB0_2194
	s_waitcnt vmcnt(0)
	v_cmp_eq_u32_e32 vcc, 0, v0
	s_waitcnt vmcnt(0)
	s_barrier
	s_and_saveexec_b64 s[2:3], vcc
	s_cbranch_execz .LBB0_2193
	v_readlane_b32 s4, v251, 7
	s_waitcnt vmcnt(0) expcnt(0) lgkmcnt(0)
	s_nop 0
	v_mov_b32_e32 v1, s4
	ds_read_b32 v3, v1
	ds_read_b32 v1, v1 offset:4
	s_waitcnt lgkmcnt(1)
	v_cmp_ne_u32_e32 vcc, 0, v3
	s_cbranch_vccnz .LBB0_2161
	v_readlane_b32 s4, v251, 2
	v_readlane_b32 s5, v251, 3
	s_load_dwordx2 s[8:9], s[4:5], 0x4
	s_add_u32 s4, s78, 0x4200
	s_addc_u32 s5, s79, 0
	s_add_u32 s6, s78, 0x4400
	s_addc_u32 s7, s79, 0
	v_readlane_b32 s10, v251, 0
	s_waitcnt lgkmcnt(0)
	s_mul_i32 s33, s8, s10
	s_add_u32 s8, s78, 0x4500
	s_mul_i32 s33, s33, s9
	s_addc_u32 s9, s79, 0
	v_readlane_b32 s11, v251, 1
	s_add_u32 s10, s78, 0x4600
	s_addc_u32 s11, s79, 0
	s_add_u32 s12, s78, 0x4700
	s_addc_u32 s13, s79, 0
	s_add_u32 s14, s78, 0x4800
	s_addc_u32 s15, s79, 0
	s_add_u32 s16, s78, 0x4900
	s_addc_u32 s17, s79, 0
	s_add_u32 s18, s78, 0x4a00
	s_addc_u32 s19, s79, 0
	s_add_u32 s20, s78, 0x4b00
	s_addc_u32 s21, s79, 0
	s_add_u32 s22, s78, 0x4c00
	s_addc_u32 s23, s79, 0
	s_add_u32 s24, s78, 0x4d00
	s_addc_u32 s25, s79, 0
	s_add_u32 s26, s78, 0x4e00
	s_addc_u32 s27, s79, 0
	s_add_u32 s28, s78, 0x4f00
	s_addc_u32 s29, s79, 0
	s_add_u32 s30, s78, 0x5000
	s_addc_u32 s31, s79, 0
	s_add_u32 s34, s78, 0x5100
	s_addc_u32 s35, s79, 0
	s_add_u32 s36, s78, 0x5200
	s_addc_u32 s37, s79, 0
	s_add_u32 s38, s78, 0x5300
	s_addc_u32 s39, s79, 0
	s_mov_b32 s46, 1
	v_mov_b32_e32 v17, 0
	s_branch .LBB0_2149
